# previous + layer-0 in-projection split moved from 28/37 to 26/39 column tiles so the out-proj phase fits three tile rounds
# speedup vs baseline: 1.0418x; 1.0086x over previous
; DI int TID() { int t = threadIdx.x; asm volatile("" : "+v"(t)); return t; }
; DI void phase_gemm(const Params& p, int g, int kind, char* smem, float* rsl, int* s_item, int vlo, int vhi, int cslot) {
;     ...
;       __syncthreads();
;       if (TID() == 0) *s_item = atomicAdd(qctr, 1);
;       __syncthreads();
;       const int kq = *s_item;
;       const int tile = ((kq >> 6) * 8 + xcd) * 64 + (kq & 63);
;       if (tile >= total) { d.ok = false; return; }
;       const int strip = tile / (MT * 8), rem = tile - strip * (MT * 8);
;       const int wdt = min(8, nvt - strip * 8);
;       const int mt = rem / wdt, vt = vlo + strip * 8 + rem % wdt;
;       d.nt = kind == 0 ? nt_map0(vt) : vt; d.m0 = mt * 128; d.n0 = d.nt * 256;
;       if (kind == 0) { d.A = (const bfu*)(G + L0_H) + (long)d.m0 * 2048; d.Bt = P_WA + (long)d.n0 * 2048; d.K = 2048; }
.LBB0_187:
	s_or_b64 exec, exec, s[2:3]
	v_mov_b32_e32 v0, 0x122d0
	s_waitcnt lgkmcnt(0)
	s_barrier
	ds_read_b32 v0, v0
	s_waitcnt lgkmcnt(0)
	v_readfirstlane_b32 s2, v0
	s_lshr_b32 s3, s2, 2
	s_lshl_b32 s3, s3, 3
	s_or_b32 s3, s3, s33
	s_and_b32 s2, s2, 3
	s_lshl_b32 s3, s3, 2
	s_or_b32 s2, s3, s2
	s_cmpk_lt_i32 s2, 0x3a8
	s_cselect_b64 s[4:5], -1, 0
	s_cmpk_gt_i32 s2, 0x3a7
	s_cbranch_scc1 .LBB0_189
	s_mul_hi_i32 s3, s2, 0x38e38e39
	s_lshr_b32 s6, s3, 31
	s_ashr_i32 s3, s3, 6
	s_add_i32 s3, s3, s6
	s_lshl_b32 s6, s3, 3
	s_sub_i32 s7, 26, s6
	s_min_u32 s7, s7, 8
	v_cvt_f32_ubyte0_e32 v0, s7
	v_rcp_iflag_f32_e32 v0, v0
	s_sub_i32 s9, 0, s7
	s_mulk_i32 s3, 0xfee0
	s_add_i32 s3, s3, s2
	v_mul_f32_e32 v0, 0x4f7ffffe, v0
	v_cvt_u32_f32_e32 v0, v0
	s_abs_i32 s8, s3
	s_ashr_i32 s2, s3, 31
	v_readfirstlane_b32 s10, v0
	s_mul_i32 s9, s9, s10
	s_mul_hi_u32 s9, s10, s9
	s_add_i32 s10, s10, s9
	s_mul_hi_u32 s9, s8, s10
	s_mul_i32 s10, s9, s7
	s_sub_i32 s8, s8, s10
	s_add_i32 s10, s9, 1
	s_sub_i32 s11, s8, s7
	s_cmp_ge_u32 s8, s7
	s_cselect_b32 s9, s10, s9
	s_cselect_b32 s8, s11, s8
	s_add_i32 s10, s9, 1
	s_cmp_ge_u32 s8, s7
	s_cselect_b32 s8, s10, s9
	s_xor_b32 s8, s8, s2
	s_sub_i32 s2, s8, s2
	s_mul_i32 s7, s2, s7
	s_sub_i32 s3, s3, s7
	s_add_i32 s3, s3, s6
	s_add_i32 s6, s3, 24
	s_sub_i32 s7, s3, 17
	s_cmp_lg_u32 s3, 16
	s_cselect_b32 s7, s7, 64
	s_cmp_lt_i32 s3, 16
	s_cselect_b32 s94, s6, s7
	s_lshl_b32 s30, s2, 7
	s_ashr_i32 s31, s30, 31
	s_lshl_b32 s34, s94, 8
	s_lshl_b64 s[2:3], s[30:31], 12
	s_add_u32 s2, s0, s2
	s_addc_u32 s3, s1, s3
	s_add_u32 s36, s2, 0xea00000
	s_addc_u32 s37, s3, 0
	s_ashr_i32 s35, s34, 31
	s_lshl_b64 s[2:3], s[34:35], 12
	v_readlane_b32 s6, v254, 13
	s_add_u32 s38, s6, s2
	v_readlane_b32 s2, v254, 14
	s_addc_u32 s39, s2, s3
	v_cndmask_b32_e64 v0, 0, 1, s[4:5]
	v_cmp_ne_u32_e64 s[2:3], 1, v0
	s_andn2_b64 vcc, exec, s[4:5]
	s_cbranch_vccnz .LBB0_191
	s_branch .LBB0_190

; DI int TID() { int t = threadIdx.x; asm volatile("" : "+v"(t)); return t; }
; DI void phase_gemm(const Params& p, int g, int kind, char* smem, float* rsl, int* s_item, int vlo, int vhi, int cslot) {
;     ...
;       __syncthreads();
;       if (TID() == 0) *s_item = atomicAdd(qctr, 1);
;       __syncthreads();
;       const int kq = *s_item;
;       const int tile = ((kq >> 6) * 8 + xcd) * 64 + (kq & 63);
;       if (tile >= total) { d.ok = false; return; }
;       const int strip = tile / (MT * 8), rem = tile - strip * (MT * 8);
;       const int wdt = min(8, nvt - strip * 8);
;       const int mt = rem / wdt, vt = vlo + strip * 8 + rem % wdt;
;       d.nt = kind == 0 ? nt_map0(vt) : vt; d.m0 = mt * 128; d.n0 = d.nt * 256;
;       if (kind == 0) { d.A = (const bfu*)(G + L0_H) + (long)d.m0 * 2048; d.Bt = P_WA + (long)d.n0 * 2048; d.K = 2048; }
.LBB0_201:
	s_or_b64 exec, exec, s[2:3]
	s_waitcnt lgkmcnt(0)
	s_barrier
	ds_read_b32 v176, v183
	s_waitcnt lgkmcnt(0)
	v_readfirstlane_b32 s1, v176
	s_lshr_b32 s2, s1, 2
	s_lshl_b32 s2, s2, 3
	s_or_b32 s2, s2, s33
	s_and_b32 s1, s1, 3
	s_lshl_b32 s2, s2, 2
	s_or_b32 s1, s2, s1
	s_cmpk_lt_i32 s1, 0x3a8
	s_cselect_b64 s[2:3], -1, 0
	s_cmpk_gt_i32 s1, 0x3a7
	s_cselect_b64 s[50:51], -1, 0
	s_and_b64 vcc, exec, s[50:51]
	s_cbranch_vccnz .LBB0_203
	s_mul_hi_i32 s4, s1, 0x38e38e39
	s_lshr_b32 s5, s4, 31
	s_ashr_i32 s4, s4, 6
	s_add_i32 s4, s4, s5
	s_lshl_b32 s5, s4, 3
	s_sub_i32 s6, 26, s5
	s_min_u32 s6, s6, 8
	v_cvt_f32_ubyte0_e32 v176, s6
	v_rcp_iflag_f32_e32 v176, v176
	s_sub_i32 s8, 0, s6
	s_mulk_i32 s4, 0xfee0
	s_add_i32 s4, s4, s1
	v_mul_f32_e32 v176, 0x4f7ffffe, v176
	v_cvt_u32_f32_e32 v176, v176
	s_abs_i32 s7, s4
	s_ashr_i32 s1, s4, 31
	v_readfirstlane_b32 s9, v176
	s_mul_i32 s8, s8, s9
	s_mul_hi_u32 s8, s9, s8
	s_add_i32 s9, s9, s8
	s_mul_hi_u32 s8, s7, s9
	s_mul_i32 s9, s8, s6
	s_sub_i32 s7, s7, s9
	s_add_i32 s9, s8, 1
	s_sub_i32 s10, s7, s6
	s_cmp_ge_u32 s7, s6
	s_cselect_b32 s8, s9, s8
	s_cselect_b32 s7, s10, s7
	s_add_i32 s9, s8, 1
	s_cmp_ge_u32 s7, s6
	s_cselect_b32 s7, s9, s8
	s_xor_b32 s7, s7, s1
	s_sub_i32 s1, s7, s1
	s_mul_i32 s6, s1, s6
	s_sub_i32 s4, s4, s6
	s_add_i32 s4, s4, s5
	s_add_i32 s5, s4, 24
	s_sub_i32 s6, s4, 17
	s_cmp_lg_u32 s4, 16
	s_cselect_b32 s6, s6, 64
	s_cmp_lt_i32 s4, 16
	s_cselect_b32 s94, s5, s6
	s_lshl_b32 s30, s1, 7
	s_ashr_i32 s31, s30, 31
	s_lshl_b32 s34, s94, 8
	s_lshl_b64 s[4:5], s[30:31], 12
	s_add_u32 s36, s61, s4
	s_addc_u32 s37, s64, s5
	s_ashr_i32 s35, s34, 31
	s_lshl_b64 s[4:5], s[34:35], 12
	v_readlane_b32 s1, v254, 13
	s_add_u32 s38, s1, s4
	v_readlane_b32 s1, v254, 14
	s_addc_u32 s39, s1, s5

; DI int TID() { int t = threadIdx.x; asm volatile("" : "+v"(t)); return t; }
; DI void phase_gemm(const Params& p, int g, int kind, char* smem, float* rsl, int* s_item, int vlo, int vhi, int cslot) {
;     ...
;       __syncthreads();
;       if (TID() == 0) *s_item = atomicAdd(qctr, 1);
;       __syncthreads();
;       const int kq = *s_item;
;       const int tile = ((kq >> 6) * 8 + xcd) * 64 + (kq & 63);
;       if (tile >= total) { d.ok = false; return; }
;       const int strip = tile / (MT * 8), rem = tile - strip * (MT * 8);
;       const int wdt = min(8, nvt - strip * 8);
;       const int mt = rem / wdt, vt = vlo + strip * 8 + rem % wdt;
;       d.nt = kind == 0 ? nt_map0(vt) : vt; d.m0 = mt * 128; d.n0 = d.nt * 256;
;       if (kind == 0) { d.A = (const bfu*)(G + L0_H) + (long)d.m0 * 2048; d.Bt = P_WA + (long)d.n0 * 2048; d.K = 2048; }
.LBB0_518:
	s_or_b64 exec, exec, s[2:3]
	s_waitcnt lgkmcnt(0)
	s_barrier
	ds_read_b32 v0, v191
	s_waitcnt lgkmcnt(0)
	v_readfirstlane_b32 s2, v0
	s_lshr_b32 s3, s2, 2
	s_lshl_b32 s3, s3, 3
	s_or_b32 s3, s3, s33
	s_and_b32 s2, s2, 3
	s_lshl_b32 s3, s3, 2
	s_or_b32 s4, s3, s2
	s_cmpk_lt_i32 s4, 0x57c
	s_cselect_b64 s[2:3], -1, 0
	s_cmpk_gt_i32 s4, 0x57b
	s_cbranch_scc1 .LBB0_524
	s_mul_hi_i32 s5, s4, 0x38e38e39
	s_lshr_b32 s6, s5, 31
	s_ashr_i32 s5, s5, 6
	s_add_i32 s5, s5, s6
	s_lshl_b32 s7, s5, 3
	s_sub_i32 s6, 39, s7
	s_min_u32 s8, s6, 8
	v_cvt_f32_ubyte0_e32 v0, s8
	v_rcp_iflag_f32_e32 v0, v0
	s_sub_i32 s9, 0, s8
	s_mulk_i32 s5, 0xfee0
	s_add_i32 s5, s5, s4
	v_mul_f32_e32 v0, 0x4f7ffffe, v0
	v_cvt_u32_f32_e32 v0, v0
	s_abs_i32 s6, s5
	s_ashr_i32 s4, s5, 31
	v_readfirstlane_b32 s10, v0
	s_mul_i32 s9, s9, s10
	s_mul_hi_u32 s9, s10, s9
	s_add_i32 s10, s10, s9
	s_mul_hi_u32 s9, s6, s10
	s_mul_i32 s10, s9, s8
	s_sub_i32 s6, s6, s10
	s_add_i32 s10, s9, 1
	s_sub_i32 s11, s6, s8
	s_cmp_ge_u32 s6, s8
	s_cselect_b32 s9, s10, s9
	s_cselect_b32 s6, s11, s6
	s_add_i32 s10, s9, 1
	s_cmp_ge_u32 s6, s8
	s_cselect_b32 s6, s10, s9
	s_xor_b32 s6, s6, s4
	s_sub_i32 s6, s6, s4
	s_mul_i32 s4, s6, s8
	s_sub_i32 s4, s5, s4
	s_add_i32 s7, s7, s4
	s_add_i32 s7, s7, 26
	s_cmp_gt_i32 s7, 15
	s_mov_b64 s[4:5], -1
	s_cbranch_scc0 .LBB0_521
	s_cmp_lt_u32 s7, 41
	s_cselect_b32 s4, 0xffffffef, -1
	s_add_i32 s4, s4, s7
	s_cmp_lg_u32 s7, 16
	s_cselect_b32 s16, s4, 64
	s_mov_b64 s[4:5], 0

; DI int TID() { int t = threadIdx.x; asm volatile("" : "+v"(t)); return t; }
; DI void phase_gemm(const Params& p, int g, int kind, char* smem, float* rsl, int* s_item, int vlo, int vhi, int cslot) {
;     ...
;       __syncthreads();
;       if (TID() == 0) *s_item = atomicAdd(qctr, 1);
;       __syncthreads();
;       const int kq = *s_item;
;       const int tile = ((kq >> 6) * 8 + xcd) * 64 + (kq & 63);
;       if (tile >= total) { d.ok = false; return; }
;       const int strip = tile / (MT * 8), rem = tile - strip * (MT * 8);
;       const int wdt = min(8, nvt - strip * 8);
;       const int mt = rem / wdt, vt = vlo + strip * 8 + rem % wdt;
;       d.nt = kind == 0 ? nt_map0(vt) : vt; d.m0 = mt * 128; d.n0 = d.nt * 256;
;       if (kind == 0) { d.A = (const bfu*)(G + L0_H) + (long)d.m0 * 2048; d.Bt = P_WA + (long)d.n0 * 2048; d.K = 2048; }
.LBB0_536:
	s_or_b64 exec, exec, s[2:3]
	s_waitcnt lgkmcnt(0)
	s_barrier
	ds_read_b32 v128, v191
	s_waitcnt lgkmcnt(0)
	v_readfirstlane_b32 s1, v128
	s_lshr_b32 s2, s1, 2
	s_lshl_b32 s2, s2, 3
	s_or_b32 s2, s2, s33
	s_and_b32 s1, s1, 3
	s_lshl_b32 s2, s2, 2
	s_or_b32 s1, s2, s1
	s_cmpk_lt_i32 s1, 0x57c
	s_cselect_b64 s[2:3], -1, 0
	s_cmpk_gt_i32 s1, 0x57b
	s_cselect_b64 s[46:47], -1, 0
	s_and_b64 vcc, exec, s[46:47]
	s_cbranch_vccnz .LBB0_543
	s_mul_hi_i32 s4, s1, 0x38e38e39
	s_lshr_b32 s5, s4, 31
	s_ashr_i32 s4, s4, 6
	s_add_i32 s4, s4, s5
	s_lshl_b32 s5, s4, 3
	s_sub_i32 s6, 39, s5
	s_min_u32 s6, s6, 8
	v_cvt_f32_ubyte0_e32 v128, s6
	v_rcp_iflag_f32_e32 v128, v128
	s_sub_i32 s13, 0, s6
	s_mulk_i32 s4, 0xfee0
	s_add_i32 s4, s4, s1
	v_mul_f32_e32 v128, 0x4f7ffffe, v128
	v_cvt_u32_f32_e32 v128, v128
	s_abs_i32 s7, s4
	s_ashr_i32 s1, s4, 31
	v_readfirstlane_b32 s14, v128
	s_mul_i32 s13, s13, s14
	s_mul_hi_u32 s13, s14, s13
	s_add_i32 s14, s14, s13
	s_mul_hi_u32 s13, s7, s14
	s_mul_i32 s14, s13, s6
	s_sub_i32 s7, s7, s14
	s_add_i32 s14, s13, 1
	s_sub_i32 s15, s7, s6
	s_cmp_ge_u32 s7, s6
	s_cselect_b32 s13, s14, s13
	s_cselect_b32 s7, s15, s7
	s_add_i32 s14, s13, 1
	s_cmp_ge_u32 s7, s6
	s_cselect_b32 s7, s14, s13
	s_xor_b32 s7, s7, s1
	s_sub_i32 s1, s7, s1
	s_mul_i32 s6, s1, s6
	s_sub_i32 s4, s4, s6
	s_add_i32 s6, s5, s4
	s_add_i32 s6, s6, 26
	s_cmp_gt_i32 s6, 15
	s_mov_b64 s[4:5], -1
	s_cbranch_scc0 .LBB0_539
	s_cmp_lt_u32 s6, 41
	s_cselect_b32 s4, 0xffffffef, -1
	s_add_i32 s4, s4, s6
	s_cmp_lg_u32 s6, 16
	s_cselect_b32 s16, s4, 64
	s_mov_b64 s[4:5], 0

; DI int TID() { int t = threadIdx.x; asm volatile("" : "+v"(t)); return t; }
; DI void phase_gemm(const Params& p, int g, int kind, char* smem, float* rsl, int* s_item, int vlo, int vhi, int cslot) {
;     ...
;       __syncthreads();
;       if (TID() == 0) *s_item = atomicAdd(qctr, 1);
;       __syncthreads();
;       const int kq = *s_item;
;       const int tile = ((kq >> 6) * 8 + xcd) * 64 + (kq & 63);
;       if (tile >= total) { d.ok = false; return; }
;       const int strip = tile / (MT * 8), rem = tile - strip * (MT * 8);
;       const int wdt = min(8, nvt - strip * 8);
;       const int mt = rem / wdt, vt = vlo + strip * 8 + rem % wdt;
;       d.nt = kind == 0 ? nt_map0(vt) : vt; d.m0 = mt * 128; d.n0 = d.nt * 256;
;       if (kind == 0) { d.A = (const bfu*)(G + L0_H) + (long)d.m0 * 2048; d.Bt = P_WA + (long)d.n0 * 2048; d.K = 2048; }
.LBB0_919:
	s_or_b64 exec, exec, s[2:3]
	s_waitcnt lgkmcnt(0)
	s_barrier
	ds_read_b32 v0, v191
	v_mov_b32_e32 v242, 0xff800000
	v_mov_b32_e32 v214, 0x7fc00000
	v_mov_b32_e32 v209, 0x7f800000
	v_mov_b32_e32 v201, 0x3ecc95a3
	s_waitcnt lgkmcnt(0)
	v_readfirstlane_b32 s2, v0
	s_lshr_b32 s3, s2, 2
	s_lshl_b32 s3, s3, 3
	s_or_b32 s3, s3, s33
	s_and_b32 s2, s2, 3
	s_lshl_b32 s3, s3, 2
	s_or_b32 s4, s3, s2
	s_cmpk_lt_i32 s4, 0x3a8
	s_cselect_b64 s[2:3], -1, 0
	s_cmpk_gt_i32 s4, 0x3a7
	s_cbranch_scc1 .LBB0_921
	s_mul_hi_i32 s5, s4, 0x38e38e39
	s_lshr_b32 s6, s5, 31
	s_ashr_i32 s5, s5, 6
	s_add_i32 s5, s5, s6
	s_lshl_b32 s6, s5, 3
	s_sub_i32 s7, 26, s6
	s_min_u32 s7, s7, 8
	v_cvt_f32_ubyte0_e32 v0, s7
	v_rcp_iflag_f32_e32 v0, v0
	s_sub_i32 s9, 0, s7
	s_mulk_i32 s5, 0xfee0
	s_add_i32 s5, s5, s4
	v_mul_f32_e32 v0, 0x4f7ffffe, v0
	v_cvt_u32_f32_e32 v0, v0
	s_abs_i32 s8, s5
	s_ashr_i32 s4, s5, 31
	v_readfirstlane_b32 s10, v0
	s_mul_i32 s9, s9, s10
	s_mul_hi_u32 s9, s10, s9
	s_add_i32 s10, s10, s9
	s_mul_hi_u32 s9, s8, s10
	s_mul_i32 s10, s9, s7
	s_sub_i32 s8, s8, s10
	s_add_i32 s10, s9, 1
	s_sub_i32 s11, s8, s7
	s_cmp_ge_u32 s8, s7
	s_cselect_b32 s9, s10, s9
	s_cselect_b32 s8, s11, s8
	s_add_i32 s10, s9, 1
	s_cmp_ge_u32 s8, s7
	s_cselect_b32 s8, s10, s9
	s_xor_b32 s8, s8, s4
	s_sub_i32 s4, s8, s4
	s_mul_i32 s7, s4, s7
	s_sub_i32 s5, s5, s7
	s_add_i32 s5, s5, s6
	s_add_i32 s6, s5, 24
	s_sub_i32 s7, s5, 17
	s_cmp_lg_u32 s5, 16
	s_cselect_b32 s7, s7, 64
	s_cmp_lt_i32 s5, 16
	s_cselect_b32 s14, s6, s7
	s_lshl_b32 s38, s4, 7
	s_ashr_i32 s39, s38, 31
	s_lshl_b32 s40, s14, 8
	s_lshl_b64 s[4:5], s[38:39], 12
	s_add_u32 s4, s0, s4
	s_addc_u32 s5, s1, s5
	s_add_u32 s42, s4, 0xea00000
	s_addc_u32 s43, s5, 0
	s_ashr_i32 s41, s40, 31
	s_lshl_b64 s[4:5], s[40:41], 12
	v_readlane_b32 s6, v254, 13
	s_add_u32 s44, s6, s4
	v_readlane_b32 s4, v254, 14
	s_addc_u32 s45, s4, s5

; DI int TID() { int t = threadIdx.x; asm volatile("" : "+v"(t)); return t; }
; DI void phase_gemm(const Params& p, int g, int kind, char* smem, float* rsl, int* s_item, int vlo, int vhi, int cslot) {
;     ...
;       __syncthreads();
;       if (TID() == 0) *s_item = atomicAdd(qctr, 1);
;       __syncthreads();
;       const int kq = *s_item;
;       const int tile = ((kq >> 6) * 8 + xcd) * 64 + (kq & 63);
;       if (tile >= total) { d.ok = false; return; }
;       const int strip = tile / (MT * 8), rem = tile - strip * (MT * 8);
;       const int wdt = min(8, nvt - strip * 8);
;       const int mt = rem / wdt, vt = vlo + strip * 8 + rem % wdt;
;       d.nt = kind == 0 ? nt_map0(vt) : vt; d.m0 = mt * 128; d.n0 = d.nt * 256;
;       if (kind == 0) { d.A = (const bfu*)(G + L0_H) + (long)d.m0 * 2048; d.Bt = P_WA + (long)d.n0 * 2048; d.K = 2048; }
.LBB0_933:
	s_or_b64 exec, exec, s[2:3]
	s_waitcnt lgkmcnt(0)
	s_barrier
	ds_read_b32 v128, v191
	s_waitcnt lgkmcnt(0)
	v_readfirstlane_b32 s1, v128
	s_lshr_b32 s2, s1, 2
	s_lshl_b32 s2, s2, 3
	s_or_b32 s2, s2, s33
	s_and_b32 s1, s1, 3
	s_lshl_b32 s2, s2, 2
	s_or_b32 s1, s2, s1
	s_cmpk_lt_i32 s1, 0x3a8
	s_cselect_b64 s[2:3], -1, 0
	s_cmpk_gt_i32 s1, 0x3a7
	s_cselect_b64 s[46:47], -1, 0
	s_and_b64 vcc, exec, s[46:47]
	s_cbranch_vccnz .LBB0_935
	s_mul_hi_i32 s4, s1, 0x38e38e39
	s_lshr_b32 s5, s4, 31
	s_ashr_i32 s4, s4, 6
	s_add_i32 s4, s4, s5
	s_lshl_b32 s5, s4, 3
	s_sub_i32 s6, 26, s5
	s_min_u32 s6, s6, 8
	v_cvt_f32_ubyte0_e32 v128, s6
	v_rcp_iflag_f32_e32 v128, v128
	s_sub_i32 s11, 0, s6
	s_mulk_i32 s4, 0xfee0
	s_add_i32 s4, s4, s1
	v_mul_f32_e32 v128, 0x4f7ffffe, v128
	v_cvt_u32_f32_e32 v128, v128
	s_abs_i32 s7, s4
	s_ashr_i32 s1, s4, 31
	v_readfirstlane_b32 s12, v128
	s_mul_i32 s11, s11, s12
	s_mul_hi_u32 s11, s12, s11
	s_add_i32 s12, s12, s11
	s_mul_hi_u32 s11, s7, s12
	s_mul_i32 s12, s11, s6
	s_sub_i32 s7, s7, s12
	s_add_i32 s12, s11, 1
	s_sub_i32 s13, s7, s6
	s_cmp_ge_u32 s7, s6
	s_cselect_b32 s11, s12, s11
	s_cselect_b32 s7, s13, s7
	s_add_i32 s12, s11, 1
	s_cmp_ge_u32 s7, s6
	s_cselect_b32 s7, s12, s11
	s_xor_b32 s7, s7, s1
	s_sub_i32 s1, s7, s1
	s_mul_i32 s6, s1, s6
	s_sub_i32 s4, s4, s6
	s_add_i32 s4, s4, s5
	s_add_i32 s5, s4, 24
	s_sub_i32 s6, s4, 17
	s_cmp_lg_u32 s4, 16
	s_cselect_b32 s6, s6, 64
	s_cmp_lt_i32 s4, 16
	s_cselect_b32 s14, s5, s6
	s_lshl_b32 s38, s1, 7
	s_ashr_i32 s39, s38, 31
	s_lshl_b32 s40, s14, 8
	s_lshl_b64 s[4:5], s[38:39], 12
	s_add_u32 s42, s63, s4
	s_addc_u32 s43, s54, s5
	s_ashr_i32 s41, s40, 31
	s_lshl_b64 s[4:5], s[40:41], 12
	v_readlane_b32 s1, v254, 13
	s_add_u32 s44, s1, s4
	v_readlane_b32 s1, v254, 14
	s_addc_u32 s45, s1, s5
